# NSA: removed IEEE canonicalising v_max x,x feeding the softmax max tree (identity for non-sNaN)
# baseline (speedup 1.0000x reference)
; DI int crow(int r, int hi) { return (r & 3) + 8 * (r >> 2) + 4 * hi; }
; DI float xmax32(float v) { auto r = __builtin_amdgcn_permlane32_swap(__float_as_uint(v), __float_as_uint(v), false, false); return fmaxf(__uint_as_float(r[0]), __uint_as_float(r[1])); }
; #define EXP2(x) __builtin_amdgcn_exp2f(x)
; #define CMP_KLOAD(dst_, kt_) _Pragma("unroll") for (int ks = 0; ks < 4; ++ks) dst_[ks] = *(const bf16x8*)(Kc + (size_t)((kt_) * 32 + q) * 64 + 8 * hh + 16 * ks)
; #define CMP_QK(s_) do { s_ = f32x16{}; _Pragma("unroll") for (int ks = 0; ks < 4; ++ks) s_ = MFMA32(kf[ks], qf[ks], s_); } while (0)
; DI void nsa_phase(int wv, const Params& P, LAS unsigned char* lds) {
;     ...
;         for (int kt = 0; kt < ntile; ++kt) { if (kt + 1 < ntile) { CMP_KLOAD(kn, kt + 1); }
;             f32x16 s; CMP_QK(s); float mx = -1e30f;
; #pragma unroll
;             for (int i = 0; i < 16; ++i) if (kt * 32 + crow(i, hh) < nvt) mx = fmaxf(mx, s[i]);
;             mx = xmax32(mx); const float mn = fmaxf(m, mx); l *= EXP2(m - mn); m = mn;
; #pragma unroll
;             for (int i = 0; i < 16; ++i) if (kt * 32 + crow(i, hh) < nvt) l += EXP2(s[i] - mn);
; #pragma unroll
;             for (int ks = 0; ks < 4; ++ks) kf[ks] = kn[ks]; }
.LBB0_1447:
	s_or_b64 exec, exec, s[12:13]
	s_waitcnt vmcnt(0) lgkmcnt(0)
	v_mfma_f32_32x32x16_bf16 v[2:17], v[94:97], v[66:69], 0
	v_add_u32_e32 v22, s88, v126
	v_cmp_lt_i32_e64 s[12:13], v22, v98
	v_add_u32_e32 v24, 1, v22
	v_cmp_lt_i32_e64 s[10:11], v24, v98
	s_add_i32 s88, s88, 32
	s_add_i32 s89, s89, 1
	v_mov_b64_e32 v[96:97], v[52:53]
	v_mfma_f32_32x32x16_bf16 v[2:17], v[90:93], v[70:73], v[2:17]
	v_mov_b64_e32 v[92:93], v[56:57]
	v_lshl_add_u64 v[18:19], v[18:19], 0, s[76:77]
	v_mov_b64_e32 v[94:95], v[50:51]
	v_mov_b64_e32 v[90:91], v[54:55]
	v_mfma_f32_32x32x16_bf16 v[2:17], v[86:89], v[74:77], v[2:17]
	v_mov_b64_e32 v[88:89], v[60:61]
	v_mov_b64_e32 v[86:87], v[58:59]
	v_mfma_f32_32x32x16_bf16 v[2:17], v[82:85], v[78:81], v[2:17]
	v_mov_b64_e32 v[84:85], v[64:65]
	v_mov_b64_e32 v[82:83], v[62:63]
	s_nop 9
	v_max_f32_e32 v23, 0xf149f2ca, v2
	v_cndmask_b32_e64 v23, v215, v23, s[12:13]
	v_max_f32_e32 v24, v23, v3
	v_cndmask_b32_e64 v23, v23, v24, s[10:11]
	v_add_u32_e32 v24, 2, v22
	v_cmp_lt_i32_e64 s[14:15], v24, v98
	v_max_f32_e32 v24, v23, v4
	s_nop 0
	v_cndmask_b32_e64 v23, v23, v24, s[14:15]
	v_add_u32_e32 v24, 3, v22
	v_cmp_lt_i32_e64 s[16:17], v24, v98
	v_max_f32_e32 v24, v23, v5
	s_nop 0
	v_cndmask_b32_e64 v23, v23, v24, s[16:17]
	v_add_u32_e32 v24, 8, v22
	v_cmp_lt_i32_e64 s[20:21], v24, v98
	v_max_f32_e32 v24, v23, v6
	s_nop 0
	v_cndmask_b32_e64 v23, v23, v24, s[20:21]
	v_add_u32_e32 v24, 9, v22
	v_cmp_lt_i32_e64 s[18:19], v24, v98
	v_max_f32_e32 v24, v23, v7
	s_nop 0
	v_cndmask_b32_e64 v23, v23, v24, s[18:19]
	v_add_u32_e32 v24, 10, v22
	v_cmp_lt_i32_e64 s[22:23], v24, v98
	v_max_f32_e32 v24, v23, v8
	s_nop 0
	v_cndmask_b32_e64 v23, v23, v24, s[22:23]
	v_add_u32_e32 v24, 11, v22
	v_cmp_lt_i32_e64 s[24:25], v24, v98
	v_max_f32_e32 v24, v23, v9
	s_nop 0
	v_cndmask_b32_e64 v23, v23, v24, s[24:25]
	v_add_u32_e32 v24, 16, v22
	v_cmp_lt_i32_e64 s[26:27], v24, v98
	v_max_f32_e32 v24, v23, v10
	s_nop 0
	v_cndmask_b32_e64 v23, v23, v24, s[26:27]
	v_add_u32_e32 v24, 17, v22
	v_cmp_lt_i32_e64 s[28:29], v24, v98
	v_max_f32_e32 v24, v23, v11
	s_nop 0
	v_cndmask_b32_e64 v23, v23, v24, s[28:29]
	v_add_u32_e32 v24, 18, v22
	v_cmp_lt_i32_e64 s[42:43], v24, v98
	v_max_f32_e32 v24, v23, v12
	s_nop 0
	v_cndmask_b32_e64 v23, v23, v24, s[42:43]
	v_add_u32_e32 v24, 19, v22
	v_cmp_lt_i32_e64 s[38:39], v24, v98
	v_max_f32_e32 v24, v23, v13
	s_nop 0
	v_cndmask_b32_e64 v23, v23, v24, s[38:39]
	v_add_u32_e32 v24, 24, v22
	v_cmp_lt_i32_e64 s[40:41], v24, v98
	v_max_f32_e32 v24, v23, v14
	s_nop 0
	v_cndmask_b32_e64 v23, v23, v24, s[40:41]
	v_add_u32_e32 v24, 25, v22
	v_cmp_lt_i32_e64 s[34:35], v24, v98
	v_max_f32_e32 v24, v23, v15
	s_nop 0
	v_cndmask_b32_e64 v23, v23, v24, s[34:35]
	v_add_u32_e32 v24, 26, v22
	v_cmp_lt_i32_e64 s[36:37], v24, v98
	v_max_f32_e32 v25, v16, v16
	v_max_f32_e32 v24, v23, v25
	v_cndmask_b32_e64 v23, v23, v24, s[36:37]
	v_add_u32_e32 v22, 27, v22
	v_cmp_lt_i32_e64 s[30:31], v22, v98
	v_max_f32_e32 v24, v17, v17
	v_max_f32_e32 v22, v23, v24
	v_cndmask_b32_e64 v22, v23, v22, s[30:31]
	v_mov_b32_e32 v23, v22
	s_nop 1
	v_permlane32_swap_b32_e32 v22, v23
	v_max3_f32 v107, v21, v22, v23
	v_sub_f32_e32 v21, v21, v107
	v_sub_f32_e32 v2, v2, v107
	v_exp_f32_e32 v21, v21
	v_exp_f32_e32 v2, v2
	v_sub_f32_e32 v3, v3, v107
	v_exp_f32_e32 v3, v3
	v_mul_f32_e32 v22, v34, v21
	v_fmac_f32_e32 v2, v34, v21
	v_cndmask_b32_e64 v2, v22, v2, s[12:13]
	v_add_f32_e32 v3, v3, v2
	v_cndmask_b32_e64 v2, v2, v3, s[10:11]
	v_sub_f32_e32 v3, v4, v107
	v_exp_f32_e32 v3, v3
	v_cmp_eq_u32_e64 s[10:11], s88, v20
	s_or_b64 s[86:87], s[10:11], s[86:87]
	v_mov_b32_e32 v21, v107
	v_add_f32_e32 v3, v3, v2
	v_cndmask_b32_e64 v2, v2, v3, s[14:15]
	v_sub_f32_e32 v3, v5, v107
	v_exp_f32_e32 v3, v3
	s_nop 0
	v_add_f32_e32 v3, v3, v2
	v_cndmask_b32_e64 v2, v2, v3, s[16:17]
	v_sub_f32_e32 v3, v6, v107
	v_exp_f32_e32 v3, v3
	s_nop 0
	v_add_f32_e32 v3, v3, v2
	v_cndmask_b32_e64 v2, v2, v3, s[20:21]
	v_sub_f32_e32 v3, v7, v107
	v_exp_f32_e32 v3, v3
	s_nop 0
	v_add_f32_e32 v3, v3, v2
	v_cndmask_b32_e64 v2, v2, v3, s[18:19]
	v_sub_f32_e32 v3, v8, v107
	v_exp_f32_e32 v3, v3
	s_nop 0
	v_add_f32_e32 v3, v3, v2
	v_cndmask_b32_e64 v2, v2, v3, s[22:23]
	v_sub_f32_e32 v3, v9, v107
	v_exp_f32_e32 v3, v3
	s_nop 0
	v_add_f32_e32 v3, v3, v2
	v_cndmask_b32_e64 v2, v2, v3, s[24:25]
	v_sub_f32_e32 v3, v10, v107
	v_exp_f32_e32 v3, v3
	s_nop 0
	v_add_f32_e32 v3, v3, v2
	v_cndmask_b32_e64 v2, v2, v3, s[26:27]
	v_sub_f32_e32 v3, v11, v107
	v_exp_f32_e32 v3, v3
	s_nop 0
	v_add_f32_e32 v3, v3, v2
	v_cndmask_b32_e64 v2, v2, v3, s[28:29]
	v_sub_f32_e32 v3, v12, v107
	v_exp_f32_e32 v3, v3
	s_nop 0
	v_add_f32_e32 v3, v3, v2
	v_cndmask_b32_e64 v2, v2, v3, s[42:43]
	v_sub_f32_e32 v3, v13, v107
	v_exp_f32_e32 v3, v3
	s_nop 0
	v_add_f32_e32 v3, v3, v2
	v_cndmask_b32_e64 v2, v2, v3, s[38:39]
	v_sub_f32_e32 v3, v14, v107
	v_exp_f32_e32 v3, v3
	s_nop 0
	v_add_f32_e32 v3, v3, v2
	v_cndmask_b32_e64 v2, v2, v3, s[40:41]
	v_sub_f32_e32 v3, v15, v107
	v_exp_f32_e32 v3, v3
	s_nop 0
	v_add_f32_e32 v3, v3, v2
	v_cndmask_b32_e64 v2, v2, v3, s[34:35]
	v_sub_f32_e32 v3, v16, v107
	v_exp_f32_e32 v3, v3
	s_nop 0
	v_add_f32_e32 v3, v3, v2
	v_cndmask_b32_e64 v2, v2, v3, s[36:37]
	v_sub_f32_e32 v3, v17, v107
	v_exp_f32_e32 v3, v3
	s_nop 0
	v_add_f32_e32 v3, v3, v2
	v_cndmask_b32_e64 v34, v2, v3, s[30:31]
	s_andn2_b64 exec, exec, s[86:87]
	s_cbranch_execz .LBB0_1450

; #define LAS __attribute__((address_space(3)))
; DI unsigned pk2(float lo, float hi) { f32x2 v = {lo, hi}; bf16x2_t b = __builtin_convertvector(v, bf16x2_t); return __builtin_bit_cast(unsigned, b); }
; DI float xmax32(float v) { auto r = __builtin_amdgcn_permlane32_swap(__float_as_uint(v), __float_as_uint(v), false, false); return fmaxf(__uint_as_float(r[0]), __uint_as_float(r[1])); }
; #define EXP2(x) __builtin_amdgcn_exp2f(x)
; #define MFMA32(a, b, c) __builtin_amdgcn_mfma_f32_32x32x16_bf16((a), (b), (c), 0, 0, 0)
; template <bool MASKED>
; DI void attn_step_l(AttnState& st, const LAS bf16_t* Kt, const LAS bf16_t* Vt, const bf16x8* qf, unsigned vmask, bool mine, int q, int hh) {
;     f32x16 s = f32x16{};
; #pragma unroll
;     for (int ks = 0; ks < 4; ++ks) { const bf16x8 af = *(const LAS bf16x8*)(Kt + q * KT_LD + 16 * ks + 8 * hh); s = MFMA32(af, qf[ks], s); }
;     if (MASKED) {
; #pragma unroll
;         for (int i = 0; i < 16; ++i) s[i] = ((vmask >> i) & 1u) ? s[i] : -1e30f; }
;     float mx = fmaxf(fmaxf(s[0], s[1]), fmaxf(s[2], s[3]));
; #pragma unroll
;     for (int i = 4; i < 16; i += 4) mx = fmaxf(mx, fmaxf(fmaxf(s[i], s[i + 1]), fmaxf(s[i + 2], s[i + 3])));
;     if (!MASKED) mx = mine ? mx : -1e30f;
;     mx = xmax32(mx);
;     if (__builtin_amdgcn_ballot_w64(mx > st.m) != 0ull) { const float mn = fmaxf(st.m, mx), al = EXP2(st.m - mn); st.m = mn; st.l *= al;
; #pragma unroll
;         for (int i = 0; i < 16; ++i) { st.o[0][i] *= al; st.o[1][i] *= al; } }
;     const float c = (MASKED || mine) ? fmaxf(st.m, -1e29f) : 1e30f;
;     float p[16]; float sum = 0.f;
; #pragma unroll
;     for (int i = 0; i < 16; ++i) { p[i] = EXP2(s[i] - c); sum += p[i]; }
;     st.l += sum;
; #pragma unroll
;     for (int s2 = 0; s2 < 2; ++s2) { u32x4 pw; pw.x = pk2(p[8 * s2], p[8 * s2 + 1]); pw.y = pk2(p[8 * s2 + 2], p[8 * s2 + 3]); pw.z = pk2(p[8 * s2 + 4], p[8 * s2 + 5]); pw.w = pk2(p[8 * s2 + 6], p[8 * s2 + 7]);
;         const bf16x8 pf = __builtin_bit_cast(bf16x8, pw);
; #pragma unroll
;         for (int dt = 0; dt < 2; ++dt) { const LAS bf16_t* vp = Vt + (dt * 32 + q) * VT_LD + 16 * s2 + 4 * hh; const u32x2 lo = *(const LAS u32x2*)vp, hi = *(const LAS u32x2*)(vp + 8);
;             const u32x4 av = (u32x4){lo.x, lo.y, hi.x, hi.y}; st.o[dt] = MFMA32(__builtin_bit_cast(bf16x8, av), pf, st.o[dt]); } }
.LBB0_1598:
	ds_read_b128 v[34:37], v221
	ds_read_b128 v[224:227], v221 offset:32
	v_and_b32_e32 v0, 1, v230
	v_and_b32_e32 v223, 2, v230
	v_cmp_eq_u32_e32 vcc, 1, v0
	s_waitcnt lgkmcnt(0)
	v_mfma_f32_32x32x16_bf16 v[34:49], v[34:37], v[66:69], 0
	v_and_b32_e32 v231, 4, v230
	v_and_b32_e32 v236, 8, v230
	v_and_b32_e32 v237, 16, v230
	v_and_b32_e32 v238, 64, v230
	v_and_b32_e32 v239, 0x80, v230
	v_and_b32_e32 v240, 0x100, v230
	v_and_b32_e32 v241, 0x200, v230
	v_mfma_f32_32x32x16_bf16 v[34:49], v[224:227], v[70:73], v[34:49]
	ds_read_b128 v[224:227], v221 offset:64
	ds_read_b128 v[232:235], v221 offset:96
	v_and_b32_e32 v242, 0x400, v230
	v_and_b32_e32 v243, 0x800, v230
	v_and_b32_e32 v0, 0x1000, v230
	s_waitcnt lgkmcnt(0)
	v_mfma_f32_32x32x16_bf16 v[34:49], v[224:227], v[74:77], v[34:49]
	v_and_b32_e32 v224, 32, v230
	v_mfma_f32_32x32x16_bf16 v[34:49], v[232:235], v[78:81], v[34:49]
	s_nop 11
	v_cndmask_b32_e32 v229, v215, v34, vcc
	v_cmp_ne_u32_e32 vcc, 0, v223
	s_nop 1
	v_cndmask_b32_e32 v228, v215, v35, vcc
	v_cmp_ne_u32_e32 vcc, 0, v231
	s_nop 1
	v_cndmask_b32_e32 v227, v215, v36, vcc
	v_cmp_ne_u32_e32 vcc, 0, v236
	s_nop 1
	v_cndmask_b32_e32 v226, v215, v37, vcc
	v_cmp_ne_u32_e32 vcc, 0, v237
	s_nop 1
	v_cndmask_b32_e32 v225, v215, v38, vcc
	v_cmp_ne_u32_e32 vcc, 0, v224
	s_nop 1
	v_cndmask_b32_e32 v224, v215, v39, vcc
	v_cmp_ne_u32_e32 vcc, 0, v238
	s_nop 1
	v_cndmask_b32_e32 v223, v215, v40, vcc
	v_cmp_ne_u32_e32 vcc, 0, v239
	s_nop 1
	v_cndmask_b32_e32 v41, v215, v41, vcc
	v_cmp_ne_u32_e32 vcc, 0, v240
	s_nop 1
	v_cndmask_b32_e32 v40, v215, v42, vcc
	v_cmp_ne_u32_e32 vcc, 0, v241
	s_nop 0
	s_nop 0
	v_cndmask_b32_e32 v39, v215, v43, vcc
	v_cmp_ne_u32_e32 vcc, 0, v242
	v_max_f32_e32 v42, v229, v228
	s_nop 0
	v_cndmask_b32_e32 v38, v215, v44, vcc
	v_cmp_ne_u32_e32 vcc, 0, v243
	s_nop 1
	v_cndmask_b32_e32 v37, v215, v45, vcc
	v_cmp_ne_u32_e32 vcc, 0, v0
	v_and_b32_e32 v0, 0x2000, v230
	v_max_f32_e32 v43, v227, v226
	v_cndmask_b32_e32 v34, v215, v46, vcc
	v_cmp_ne_u32_e32 vcc, 0, v0
	v_and_b32_e32 v0, 0x4000, v230
	s_nop 0
	v_cndmask_b32_e32 v35, v215, v47, vcc
	v_cmp_ne_u32_e32 vcc, 0, v0
	v_and_b32_e32 v0, 0x8000, v230
	v_max_f32_e32 v44, v223, v41
	v_cndmask_b32_e32 v36, v215, v48, vcc
	v_cmp_ne_u32_e32 vcc, 0, v0
	v_max3_f32 v44, v225, v224, v44
	v_max3_f32 v42, v42, v43, v44
	v_cndmask_b32_e32 v0, v215, v49, vcc
	v_max_f32_e32 v43, v38, v37
	v_max_f32_e32 v44, v36, v0
	v_max3_f32 v43, v40, v39, v43
	v_max3_f32 v44, v34, v35, v44
	v_max3_f32 v42, v42, v43, v44
	v_mov_b32_e32 v43, v42
	s_nop 1
	v_permlane32_swap_b32_e32 v42, v43
	v_max_f32_e32 v42, v42, v43
	v_cmp_gt_f32_e32 vcc, v42, v222
	s_cbranch_vccz .LBB0_1600
	v_max_f32_e32 v43, v222, v42
	v_sub_f32_e32 v42, v222, v43
	v_exp_f32_e32 v42, v42
	v_mov_b32_e32 v222, v43
	v_mul_f32_e32 v219, v219, v42
	v_pk_mul_f32 v[32:33], v[32:33], v[42:43] op_sel_hi:[1,0]
	v_pk_mul_f32 v[30:31], v[30:31], v[42:43] op_sel_hi:[1,0]
	v_pk_mul_f32 v[28:29], v[28:29], v[42:43] op_sel_hi:[1,0]
	v_pk_mul_f32 v[26:27], v[26:27], v[42:43] op_sel_hi:[1,0]
	v_pk_mul_f32 v[24:25], v[24:25], v[42:43] op_sel_hi:[1,0]
	v_pk_mul_f32 v[22:23], v[22:23], v[42:43] op_sel_hi:[1,0]
	v_pk_mul_f32 v[20:21], v[20:21], v[42:43] op_sel_hi:[1,0]
	v_pk_mul_f32 v[18:19], v[18:19], v[42:43] op_sel_hi:[1,0]
	v_pk_mul_f32 v[16:17], v[16:17], v[42:43] op_sel_hi:[1,0]
	v_pk_mul_f32 v[14:15], v[14:15], v[42:43] op_sel_hi:[1,0]
	v_pk_mul_f32 v[12:13], v[12:13], v[42:43] op_sel_hi:[1,0]
	v_pk_mul_f32 v[10:11], v[10:11], v[42:43] op_sel_hi:[1,0]
	v_pk_mul_f32 v[8:9], v[8:9], v[42:43] op_sel_hi:[1,0]
	v_pk_mul_f32 v[6:7], v[6:7], v[42:43] op_sel_hi:[1,0]
	v_pk_mul_f32 v[4:5], v[4:5], v[42:43] op_sel_hi:[1,0]
	v_pk_mul_f32 v[2:3], v[2:3], v[42:43] op_sel_hi:[1,0]
.LBB0_1600:
	v_max_f32_e32 v230, 0xefa18f08, v222
	v_sub_f32_e32 v42, v229, v230
	v_exp_f32_e32 v42, v42
	v_sub_f32_e32 v43, v228, v230
	v_exp_f32_e32 v43, v43
	v_sub_f32_e32 v44, v227, v230
	v_exp_f32_e32 v44, v44
	v_sub_f32_e32 v46, v226, v230
	v_exp_f32_e32 v46, v46
	v_sub_f32_e32 v47, v225, v230
	v_add_f32_e32 v45, 0, v42
	v_exp_f32_e32 v47, v47
	v_sub_f32_e32 v48, v224, v230
	v_add_f32_e32 v45, v43, v45
	v_exp_f32_e32 v48, v48
	v_sub_f32_e32 v49, v223, v230
	v_add_f32_e32 v45, v44, v45
	v_exp_f32_e32 v49, v49
	v_sub_f32_e32 v41, v41, v230
	v_add_f32_e32 v45, v46, v45
	v_exp_f32_e32 v223, v41
	v_sub_f32_e32 v40, v40, v230
	v_add_f32_e32 v45, v47, v45
	v_exp_f32_e32 v224, v40
	v_sub_f32_e32 v39, v39, v230
	v_add_f32_e32 v45, v48, v45
	v_exp_f32_e32 v225, v39
	v_add_f32_e32 v39, v49, v45
	v_add_f32_e32 v39, v223, v39
	v_add_f32_e32 v39, v224, v39
	v_sub_f32_e32 v38, v38, v230
	v_cvt_pk_bf16_f32 v45, v49, v223
	v_add_u32_e32 v223, 0x2000, v195
	v_add_f32_e32 v226, v225, v39
	v_exp_f32_e32 v227, v38
	ds_read2_b64 v[38:41], v195 offset1:2
	v_cvt_pk_bf16_f32 v42, v42, v43
	v_cvt_pk_bf16_f32 v43, v44, v46
	v_cvt_pk_bf16_f32 v44, v47, v48
	ds_read2_b64 v[46:49], v223 offset0:64 offset1:66
	v_sub_f32_e32 v34, v34, v230
	v_exp_f32_e32 v229, v34
	v_sub_f32_e32 v34, v35, v230
	v_sub_f32_e32 v37, v37, v230
	v_exp_f32_e32 v231, v34
	v_sub_f32_e32 v34, v36, v230
	v_exp_f32_e32 v228, v37
	s_waitcnt lgkmcnt(0)
	v_mfma_f32_32x32x16_bf16 v[18:33], v[38:41], v[42:45], v[18:33]
	v_exp_f32_e32 v232, v34
	ds_read2_b64 v[34:37], v195 offset0:4 offset1:6
	v_sub_f32_e32 v0, v0, v230
	v_exp_f32_e32 v0, v0
	v_cvt_pk_bf16_f32 v38, v224, v225
	v_cvt_pk_bf16_f32 v39, v227, v228
	v_cvt_pk_bf16_f32 v40, v229, v231
	v_mfma_f32_32x32x16_bf16 v[2:17], v[46:49], v[42:45], v[2:17]
	ds_read2_b64 v[42:45], v223 offset0:68 offset1:70
	v_cvt_pk_bf16_f32 v41, v232, v0
	s_waitcnt lgkmcnt(0)
	s_nop 0
	v_mfma_f32_32x32x16_bf16 v[18:33], v[34:37], v[38:41], v[18:33]
	v_add_f32_e32 v34, v227, v226
	v_add_f32_e32 v34, v228, v34
	v_add_f32_e32 v34, v229, v34
	v_add_f32_e32 v34, v231, v34
	v_add_f32_e32 v34, v232, v34
	v_add_f32_e32 v0, v0, v34
	v_add_f32_e32 v219, v219, v0
	v_mfma_f32_32x32x16_bf16 v[2:17], v[42:45], v[38:41], v[2:17]
; #define LAS __attribute__((address_space(3)))
; DI unsigned pk2(float lo, float hi) { f32x2 v = {lo, hi}; bf16x2_t b = __builtin_convertvector(v, bf16x2_t); return __builtin_bit_cast(unsigned, b); }
; DI float xmax32(float v) { auto r = __builtin_amdgcn_permlane32_swap(__float_as_uint(v), __float_as_uint(v), false, false); return fmaxf(__uint_as_float(r[0]), __uint_as_float(r[1])); }
; #define EXP2(x) __builtin_amdgcn_exp2f(x)
; #define MFMA32(a, b, c) __builtin_amdgcn_mfma_f32_32x32x16_bf16((a), (b), (c), 0, 0, 0)
; template <bool MASKED>
; DI void attn_step_l(AttnState& st, const LAS bf16_t* Kt, const LAS bf16_t* Vt, const bf16x8* qf, unsigned vmask, bool mine, int q, int hh) {
;     f32x16 s = f32x16{};
; #pragma unroll
;     for (int ks = 0; ks < 4; ++ks) { const bf16x8 af = *(const LAS bf16x8*)(Kt + q * KT_LD + 16 * ks + 8 * hh); s = MFMA32(af, qf[ks], s); }
;     if (MASKED) {
; #pragma unroll
;         for (int i = 0; i < 16; ++i) s[i] = ((vmask >> i) & 1u) ? s[i] : -1e30f; }
;     float mx = fmaxf(fmaxf(s[0], s[1]), fmaxf(s[2], s[3]));
; #pragma unroll
;     for (int i = 4; i < 16; i += 4) mx = fmaxf(mx, fmaxf(fmaxf(s[i], s[i + 1]), fmaxf(s[i + 2], s[i + 3])));
;     if (!MASKED) mx = mine ? mx : -1e30f;
;     mx = xmax32(mx);
;     if (__builtin_amdgcn_ballot_w64(mx > st.m) != 0ull) { const float mn = fmaxf(st.m, mx), al = EXP2(st.m - mn); st.m = mn; st.l *= al;
; #pragma unroll
;         for (int i = 0; i < 16; ++i) { st.o[0][i] *= al; st.o[1][i] *= al; } }
;     const float c = (MASKED || mine) ? fmaxf(st.m, -1e29f) : 1e30f;
;     float p[16]; float sum = 0.f;
; #pragma unroll
;     for (int i = 0; i < 16; ++i) { p[i] = EXP2(s[i] - c); sum += p[i]; }
;     st.l += sum;
; #pragma unroll
;     for (int s2 = 0; s2 < 2; ++s2) { u32x4 pw; pw.x = pk2(p[8 * s2], p[8 * s2 + 1]); pw.y = pk2(p[8 * s2 + 2], p[8 * s2 + 3]); pw.z = pk2(p[8 * s2 + 4], p[8 * s2 + 5]); pw.w = pk2(p[8 * s2 + 6], p[8 * s2 + 7]);
;         const bf16x8 pf = __builtin_bit_cast(bf16x8, pw);
; #pragma unroll
;         for (int dt = 0; dt < 2; ++dt) { const LAS bf16_t* vp = Vt + (dt * 32 + q) * VT_LD + 16 * s2 + 4 * hh; const u32x2 lo = *(const LAS u32x2*)vp, hi = *(const LAS u32x2*)(vp + 8);
;             const u32x4 av = (u32x4){lo.x, lo.y, hi.x, hi.y}; st.o[dt] = MFMA32(__builtin_bit_cast(bf16x8, av), pf, st.o[dt]); } }
.LBB0_1601:
	s_andn2_saveexec_b64 s[12:13], s[26:27]
	s_cbranch_execz .LBB0_1605
	ds_read_b128 v[34:37], v221
	ds_read_b128 v[224:227], v221 offset:32
	s_waitcnt lgkmcnt(0)
	v_mfma_f32_32x32x16_bf16 v[34:49], v[34:37], v[66:69], 0
	v_mfma_f32_32x32x16_bf16 v[34:49], v[224:227], v[70:73], v[34:49]
	ds_read_b128 v[224:227], v221 offset:64
	ds_read_b128 v[228:231], v221 offset:96
	s_waitcnt lgkmcnt(0)
	v_mfma_f32_32x32x16_bf16 v[34:49], v[224:227], v[74:77], v[34:49]
	v_mfma_f32_32x32x16_bf16 v[34:49], v[228:231], v[78:81], v[34:49]
	s_nop 11
	v_max_f32_e32 v0, v34, v35
	v_max_f32_e32 v223, v36, v37
	v_max_f32_e32 v224, v40, v41
	v_max_f32_e32 v225, v44, v45
	v_max_f32_e32 v226, v48, v49
	v_max3_f32 v224, v38, v39, v224
	v_max3_f32 v225, v42, v43, v225
	v_max3_f32 v226, v46, v47, v226
	v_max3_f32 v0, v0, v223, v224
	v_max3_f32 v0, v0, v225, v226
	v_cndmask_b32_e64 v0, v215, v0, s[10:11]
	v_mov_b32_e32 v223, v0
	s_nop 1
	v_permlane32_swap_b32_e32 v0, v223
	v_max_f32_e32 v0, v0, v223
	v_cmp_gt_f32_e32 vcc, v0, v222
	s_cbranch_vccz .LBB0_1604
	v_max_f32_e32 v223, v222, v0
	v_sub_f32_e32 v0, v222, v223
	v_exp_f32_e32 v0, v0
	v_mov_b32_e32 v222, v223
	v_mul_f32_e32 v219, v219, v0
	v_pk_mul_f32 v[32:33], v[32:33], v[0:1] op_sel_hi:[1,0]
	v_pk_mul_f32 v[30:31], v[30:31], v[0:1] op_sel_hi:[1,0]
	v_pk_mul_f32 v[28:29], v[28:29], v[0:1] op_sel_hi:[1,0]
	v_pk_mul_f32 v[26:27], v[26:27], v[0:1] op_sel_hi:[1,0]
	v_pk_mul_f32 v[24:25], v[24:25], v[0:1] op_sel_hi:[1,0]
	v_pk_mul_f32 v[22:23], v[22:23], v[0:1] op_sel_hi:[1,0]
	v_pk_mul_f32 v[20:21], v[20:21], v[0:1] op_sel_hi:[1,0]
	v_pk_mul_f32 v[18:19], v[18:19], v[0:1] op_sel_hi:[1,0]
	v_pk_mul_f32 v[16:17], v[16:17], v[0:1] op_sel_hi:[1,0]
	v_pk_mul_f32 v[14:15], v[14:15], v[0:1] op_sel_hi:[1,0]
	v_pk_mul_f32 v[12:13], v[12:13], v[0:1] op_sel_hi:[1,0]
	v_pk_mul_f32 v[10:11], v[10:11], v[0:1] op_sel_hi:[1,0]
	v_pk_mul_f32 v[8:9], v[8:9], v[0:1] op_sel_hi:[1,0]
	v_pk_mul_f32 v[6:7], v[6:7], v[0:1] op_sel_hi:[1,0]
	v_pk_mul_f32 v[4:5], v[4:5], v[0:1] op_sel_hi:[1,0]
	v_pk_mul_f32 v[2:3], v[2:3], v[0:1] op_sel_hi:[1,0]
.LBB0_1604:
	v_max_f32_e32 v0, 0xefa18f08, v222
	v_cndmask_b32_e64 v0, v217, v0, s[10:11]
	v_sub_f32_e32 v34, v34, v0
	v_exp_f32_e32 v223, v34
	v_sub_f32_e32 v34, v35, v0
	v_exp_f32_e32 v224, v34
	v_sub_f32_e32 v34, v36, v0
	v_exp_f32_e32 v225, v34
	v_sub_f32_e32 v34, v37, v0
	v_add_f32_e32 v35, 0, v223
	v_exp_f32_e32 v226, v34
	v_sub_f32_e32 v34, v38, v0
	v_add_f32_e32 v35, v224, v35
	v_exp_f32_e32 v227, v34
	v_sub_f32_e32 v34, v39, v0
	v_exp_f32_e32 v228, v34
	v_add_f32_e32 v34, v225, v35
	v_sub_f32_e32 v35, v40, v0
	v_exp_f32_e32 v229, v35
	v_sub_f32_e32 v35, v41, v0
	v_add_f32_e32 v34, v226, v34
	v_exp_f32_e32 v41, v35
	v_sub_f32_e32 v35, v42, v0
	v_add_f32_e32 v34, v227, v34
	v_exp_f32_e32 v230, v35
	v_sub_f32_e32 v35, v43, v0
	v_add_f32_e32 v34, v228, v34
	v_exp_f32_e32 v231, v35
	v_add_f32_e32 v34, v229, v34
	v_add_f32_e32 v34, v41, v34
	v_add_f32_e32 v34, v230, v34
	v_add_f32_e32 v232, v231, v34
	v_sub_f32_e32 v34, v44, v0
	v_exp_f32_e32 v233, v34
	ds_read2_b64 v[34:37], v195 offset1:2
	v_sub_f32_e32 v38, v45, v0
	v_exp_f32_e32 v234, v38
	v_cvt_pk_bf16_f32 v38, v223, v224
	v_add_u32_e32 v223, 0x2000, v195
	ds_read2_b64 v[42:45], v223 offset0:64 offset1:66
	v_cvt_pk_bf16_f32 v39, v225, v226
	v_cvt_pk_bf16_f32 v40, v227, v228
	v_cvt_pk_bf16_f32 v41, v229, v41
	s_waitcnt lgkmcnt(0)
	s_nop 0
	v_mfma_f32_32x32x16_bf16 v[18:33], v[34:37], v[38:41], v[18:33]
	v_sub_f32_e32 v34, v46, v0
	v_exp_f32_e32 v46, v34
	v_sub_f32_e32 v34, v47, v0
	v_exp_f32_e32 v47, v34
	v_sub_f32_e32 v34, v48, v0
	v_exp_f32_e32 v48, v34
	ds_read2_b64 v[34:37], v195 offset0:4 offset1:6
	v_mfma_f32_32x32x16_bf16 v[2:17], v[42:45], v[38:41], v[2:17]
	ds_read2_b64 v[42:45], v223 offset0:68 offset1:70
	v_sub_f32_e32 v0, v49, v0
	v_exp_f32_e32 v0, v0
	v_cvt_pk_bf16_f32 v38, v230, v231
	v_cvt_pk_bf16_f32 v39, v233, v234
	v_cvt_pk_bf16_f32 v40, v46, v47
	v_cvt_pk_bf16_f32 v41, v48, v0
	s_waitcnt lgkmcnt(0)
	s_nop 0
	v_mfma_f32_32x32x16_bf16 v[18:33], v[34:37], v[38:41], v[18:33]
	v_add_f32_e32 v34, v233, v232
	v_add_f32_e32 v34, v234, v34
	v_add_f32_e32 v34, v46, v34
	v_add_f32_e32 v34, v47, v34
	v_add_f32_e32 v34, v48, v34
	v_add_f32_e32 v0, v0, v34
	v_add_f32_e32 v219, v219, v0
	v_mfma_f32_32x32x16_bf16 v[2:17], v[42:45], v[38:41], v[2:17]
